# adds: memory cross-attention K/V fragments staged once per workgroup in LDS (8 waves share one batch-head) with a one-tile-per-trip loop
# speedup vs baseline: 1.0081x; 1.0041x over previous
; __device__ __forceinline__ void xattn_phase(const bf16* QXB, const bf16* MKF, const bf16* MVF, bf16* OXB, int G, int tid) {
;     ...
;     for (int it = (int)blockIdx.x * (MK_THREADS / 64) + wave; it < NIT; it += G * (MK_THREADS / 64)) { const int qb = it % NQ32, bhx = it / NQ32, h = bhx % XH, b = bhx / XH;
;         const size_t row0 = (size_t)b * SEQ + 32 * qb;
;         const bf16* qp = QXB + (row0 + r32) * XW + h * XHD + 8 * hh; const bf16* kp = MKF + (size_t)(b * XH + h) * 32768 + lane * 8;
;         bf16x8 qf[8];
; #pragma unroll
;         for (int ks = 0; ks < 8; ++ks) qf[ks] = *(const bf16x8*)(qp + 16 * ks);
;         const bf16* vp = MVF + (size_t)(b * XH + h) * 32768 + lane * 16;
;         f32x16 o[4]; o[0] = f32x16{}; o[1] = f32x16{}; o[2] = f32x16{}; o[3] = f32x16{}; float m_run = -INFINITY, l_run = 0.f;
;     ...
;         bf16x8 kfa[8], kfb[8];
; #pragma unroll
;         for (int ks = 0; ks < 8; ++ks) kfa[ks] = *(const bf16x8*)(kp + ks * 512);
.LBB0_1511:
	s_ashr_i32 s0, s8, 31
	s_lshr_b32 s1, s0, 25
	s_add_i32 s1, s8, s1
	s_ashr_i32 s2, s1, 7
	s_and_b32 s1, s1, 0x7ffff80
	s_sub_i32 s6, s8, s1
	s_lshr_b32 s1, s2, 30
	s_add_i32 s1, s2, s1
	s_lshr_b32 s0, s0, 23
	s_and_b32 s1, s1, -4
	s_add_i32 s0, s8, s0
	s_sub_i32 s7, s2, s1
	s_ashr_i32 s2, s0, 9
	s_ashr_i32 s3, s2, 31
	s_lshl_b64 s[0:1], s[2:3], 12
	s_lshl_b32 s3, s6, 5
	s_ashr_i32 s6, s3, 31
	s_add_u32 s0, s0, s3
	s_addc_u32 s1, s1, s6
	v_mov_b32_e32 v3, s1
	v_or_b32_e32 v2, s0, v222
	v_readlane_b32 s0, v252, 19
	v_lshlrev_b64 v[4:5], 10, v[2:3]
	v_readlane_b32 s1, v252, 20
	s_lshl_b32 s2, s2, 2
	s_add_i32 s2, s2, s7
	v_lshl_add_u64 v[4:5], s[0:1], 0, v[4:5]
	s_lshl_b32 s0, s7, 7
	s_ashr_i32 s1, s0, 31
	v_lshl_add_u64 v[4:5], s[0:1], 1, v[4:5]
	v_lshl_add_u64 v[4:5], v[4:5], 0, v[214:215]
	s_ashr_i32 s3, s2, 31
	global_load_dwordx4 v[82:85], v[4:5], off
	global_load_dwordx4 v[86:89], v[4:5], off offset:32
	global_load_dwordx4 v[90:93], v[4:5], off offset:64
	global_load_dwordx4 v[94:97], v[4:5], off offset:96
	global_load_dwordx4 v[98:101], v[4:5], off offset:128
	global_load_dwordx4 v[102:105], v[4:5], off offset:160
	global_load_dwordx4 v[106:109], v[4:5], off offset:192
	global_load_dwordx4 v[110:113], v[4:5], off offset:224
	s_lshl_b64 s[2:3], s[2:3], 16
	v_lshl_add_u64 v[182:183], v[226:227], 0, s[2:3]
	v_mov_b32_e32 v50, v215
	v_mov_b32_e32 v51, v215
	v_lshlrev_b64 v[232:233], 9, v[2:3]
	s_add_u32 s2, s9, s2
	v_mov_b32_e32 v52, v215
	v_mov_b32_e32 v53, v215
	v_mov_b32_e32 v54, v215
	v_mov_b32_e32 v55, v215
	v_mov_b32_e32 v56, v215
	v_mov_b32_e32 v57, v215
	v_mov_b32_e32 v58, v215
	v_mov_b32_e32 v59, v215
	v_mov_b32_e32 v60, v215
	v_mov_b32_e32 v61, v215
	v_mov_b32_e32 v62, v215
	v_mov_b32_e32 v63, v215
	v_mov_b32_e32 v64, v215
	v_mov_b32_e32 v65, v215
	v_mov_b64_e32 v[34:35], v[50:51]
	v_mov_b64_e32 v[18:19], v[50:51]
	v_mov_b64_e32 v[2:3], v[50:51]
	s_mov_b32 s11, 0
	s_addc_u32 s3, s10, s3
	v_mov_b32_e32 v231, 0
	v_mov_b32_e32 v248, 0xff800000
	v_mov_b64_e32 v[36:37], v[52:53]
	v_mov_b64_e32 v[38:39], v[54:55]
	v_mov_b64_e32 v[40:41], v[56:57]
	v_mov_b64_e32 v[42:43], v[58:59]
	v_mov_b64_e32 v[44:45], v[60:61]
	v_mov_b64_e32 v[46:47], v[62:63]
	v_mov_b64_e32 v[48:49], v[64:65]
	v_mov_b64_e32 v[20:21], v[52:53]
	v_mov_b64_e32 v[22:23], v[54:55]
	v_mov_b64_e32 v[24:25], v[56:57]
	v_mov_b64_e32 v[26:27], v[58:59]
	v_mov_b64_e32 v[28:29], v[60:61]
	v_mov_b64_e32 v[30:31], v[62:63]
	v_mov_b64_e32 v[32:33], v[64:65]
	v_mov_b64_e32 v[4:5], v[52:53]
	v_mov_b64_e32 v[6:7], v[54:55]
	v_mov_b64_e32 v[8:9], v[56:57]
	v_mov_b64_e32 v[10:11], v[58:59]
	v_mov_b64_e32 v[12:13], v[60:61]
	v_mov_b64_e32 v[14:15], v[62:63]
	v_mov_b64_e32 v[16:17], v[64:65]
	s_and_b32 s6, s8, 7
	s_lshl_b32 s6, s6, 13
	s_mov_b32 s7, 0
	v_lshl_add_u64 v[182:183], s[6:7], 0, v[182:183]
	global_load_dwordx4 v[114:117], v[182:183], off
	global_load_dwordx4 v[118:121], v[182:183], off offset:1024
	global_load_dwordx4 v[122:125], v[182:183], off offset:2048
	global_load_dwordx4 v[126:129], v[182:183], off offset:3072
	v_add_co_u32_e32 v184, vcc, 0x1000, v182
	s_nop 1
	v_addc_co_u32_e32 v185, vcc, 0, v183, vcc
	global_load_dwordx4 v[130:133], v[184:185], off
	global_load_dwordx4 v[134:137], v[184:185], off offset:1024
	global_load_dwordx4 v[138:141], v[184:185], off offset:2048
	global_load_dwordx4 v[142:145], v[184:185], off offset:3072
	v_lshl_add_u64 v[186:187], s[6:7], 0, v[228:229]
	v_lshl_add_u64 v[186:187], s[2:3], 0, v[186:187]
	v_add_co_u32_e32 v186, vcc, 0x22a00000, v186
	s_nop 1
	v_addc_co_u32_e32 v187, vcc, 0, v187, vcc
	v_add_co_u32_e32 v184, vcc, 0x1000, v186
	s_nop 1
	v_addc_co_u32_e32 v185, vcc, 0, v187, vcc
	global_load_dwordx4 v[146:149], v[186:187], off
	global_load_dwordx4 v[162:165], v[186:187], off offset:16
	global_load_dwordx4 v[150:153], v[186:187], off offset:2048
	global_load_dwordx4 v[166:169], v[186:187], off offset:2064
	global_load_dwordx4 v[154:157], v[184:185], off
	global_load_dwordx4 v[170:173], v[184:185], off offset:16
	global_load_dwordx4 v[158:161], v[184:185], off offset:2048
	global_load_dwordx4 v[174:177], v[184:185], off offset:2064
	v_add_u32_e32 v188, s6, v224
	v_add_u32_e32 v189, 0x10000, v188
	s_waitcnt vmcnt(0)
	ds_write_b128 v188, v[114:117]
	ds_write_b128 v188, v[118:121] offset:1024
	ds_write_b128 v188, v[122:125] offset:2048
	ds_write_b128 v188, v[126:129] offset:3072
	ds_write_b128 v188, v[130:133] offset:4096
	ds_write_b128 v188, v[134:137] offset:5120
	ds_write_b128 v188, v[138:141] offset:6144
	ds_write_b128 v188, v[142:145] offset:7168
	ds_write_b128 v189, v[146:149]
	ds_write_b128 v189, v[162:165] offset:1024
	ds_write_b128 v189, v[150:153] offset:2048
	ds_write_b128 v189, v[166:169] offset:3072
	ds_write_b128 v189, v[154:157] offset:4096
	ds_write_b128 v189, v[170:173] offset:5120
	ds_write_b128 v189, v[158:161] offset:6144
	ds_write_b128 v189, v[174:177] offset:7168
	v_mov_b32_e32 v180, v224
	v_add_u32_e32 v181, 0x10000, v224
	s_waitcnt lgkmcnt(0)
	s_barrier
; __device__ __forceinline__ void xattn_phase(const bf16* QXB, const bf16* MKF, const bf16* MVF, bf16* OXB, int G, int tid) {
;     ...
;         bf16x8 kfa[8], kfb[8];
; #pragma unroll
;         for (int ks = 0; ks < 8; ++ks) kfa[ks] = *(const bf16x8*)(kp + ks * 512);
; #pragma unroll 1
;         for (int kt = 0; kt < 8; kt += 2) { XA_TILE(kt, kfa, kfb, true) XA_TILE(kt + 1, kfb, kfa, kt + 2 < 8) }
.Lxa_tile:
	ds_read_b128 v[114:117], v180
	ds_read_b128 v[118:121], v180 offset:1024
	ds_read_b128 v[122:125], v180 offset:2048
	ds_read_b128 v[126:129], v180 offset:3072
	ds_read_b128 v[130:133], v180 offset:4096
	ds_read_b128 v[134:137], v180 offset:5120
	ds_read_b128 v[138:141], v180 offset:6144
	ds_read_b128 v[142:145], v180 offset:7168
	s_waitcnt lgkmcnt(7)
	v_mfma_f32_32x32x16_bf16 v[66:81], v[114:117], v[82:85], 0
	ds_read_b128 v[146:149], v181
	s_waitcnt lgkmcnt(7)
	v_mfma_f32_32x32x16_bf16 v[66:81], v[118:121], v[86:89], v[66:81]
	ds_read_b128 v[162:165], v181 offset:1024
	s_waitcnt lgkmcnt(7)
	v_mfma_f32_32x32x16_bf16 v[66:81], v[122:125], v[90:93], v[66:81]
	ds_read_b128 v[150:153], v181 offset:2048
	s_waitcnt lgkmcnt(7)
	v_mfma_f32_32x32x16_bf16 v[66:81], v[126:129], v[94:97], v[66:81]
	ds_read_b128 v[166:169], v181 offset:3072
	s_waitcnt lgkmcnt(7)
	v_mfma_f32_32x32x16_bf16 v[66:81], v[130:133], v[98:101], v[66:81]
	ds_read_b128 v[154:157], v181 offset:4096
	s_waitcnt lgkmcnt(7)
	v_mfma_f32_32x32x16_bf16 v[66:81], v[134:137], v[102:105], v[66:81]
	ds_read_b128 v[170:173], v181 offset:5120
	s_waitcnt lgkmcnt(7)
	v_mfma_f32_32x32x16_bf16 v[66:81], v[138:141], v[106:109], v[66:81]
	ds_read_b128 v[158:161], v181 offset:6144
	s_waitcnt lgkmcnt(7)
	v_mfma_f32_32x32x16_bf16 v[66:81], v[142:145], v[110:113], v[66:81]
	ds_read_b128 v[174:177], v181 offset:7168
	s_nop 11
	v_med3_f32 v212, v66, v67, s89
	v_med3_f32 v212, v212, v68, s89
	v_med3_f32 v212, v212, v69, s89
	v_med3_f32 v212, v212, v70, s89
	v_med3_f32 v212, v212, v71, s89
	v_med3_f32 v212, v212, v72, s89
	v_med3_f32 v212, v212, v73, s89
	v_med3_f32 v212, v212, v74, s89
	v_med3_f32 v212, v212, v75, s89
	v_med3_f32 v212, v212, v76, s89
	v_med3_f32 v212, v212, v77, s89
	v_med3_f32 v212, v212, v78, s89
	v_med3_f32 v212, v212, v79, s89
	v_med3_f32 v212, v212, v80, s89
	v_med3_f32 v212, v212, v81, s89
	ds_bpermute_b32 v213, v247, v212
	s_waitcnt lgkmcnt(0)
	v_med3_f32 v212, v212, v213, s89
	v_mul_f32_e32 v212, 0x3e0293ee, v212
	v_max_f32_e32 v213, v248, v248
	v_max_f32_e32 v220, v213, v212
	v_fma_f32 v66, v66, s67, -v220
	v_fma_f32 v67, v67, s67, -v220
	v_fma_f32 v68, v68, s67, -v220
	v_fma_f32 v69, v69, s67, -v220
	v_fma_f32 v70, v70, s67, -v220
	v_fma_f32 v71, v71, s67, -v220
	v_fma_f32 v72, v72, s67, -v220
	v_fma_f32 v73, v73, s67, -v220
	v_fma_f32 v74, v74, s67, -v220
	v_fma_f32 v75, v75, s67, -v220
	v_fma_f32 v76, v76, s67, -v220
	v_fma_f32 v77, v77, s67, -v220
	v_fma_f32 v78, v78, s67, -v220
	v_fma_f32 v79, v79, s67, -v220
	v_fma_f32 v80, v80, s67, -v220
	v_fma_f32 v81, v81, s67, -v220
	v_exp_f32_e32 v66, v66
	v_exp_f32_e32 v67, v67
	v_add_f32_e32 v221, 0, v66
	v_exp_f32_e32 v68, v68
	v_add_f32_e32 v221, v67, v221
	v_exp_f32_e32 v69, v69
	v_add_f32_e32 v221, v68, v221
	v_exp_f32_e32 v70, v70
	v_add_f32_e32 v221, v69, v221
	v_exp_f32_e32 v71, v71
	v_add_f32_e32 v221, v70, v221
	v_exp_f32_e32 v72, v72
	v_add_f32_e32 v221, v71, v221
	v_exp_f32_e32 v73, v73
	v_add_f32_e32 v221, v72, v221
	v_exp_f32_e32 v74, v74
	v_add_f32_e32 v221, v73, v221
	v_exp_f32_e32 v75, v75
	v_add_f32_e32 v221, v74, v221
	v_exp_f32_e32 v76, v76
	v_add_f32_e32 v221, v75, v221
	v_exp_f32_e32 v77, v77
	v_add_f32_e32 v221, v76, v221
	v_exp_f32_e32 v78, v78
	v_add_f32_e32 v221, v77, v221
	v_exp_f32_e32 v79, v79
	v_add_f32_e32 v221, v78, v221
	v_exp_f32_e32 v80, v80
	v_add_f32_e32 v221, v79, v221
	v_exp_f32_e32 v81, v81
	v_add_f32_e32 v221, v80, v221
	v_sub_f32_e32 v213, v248, v220
	v_add_f32_e32 v221, v81, v221
	v_exp_f32_e32 v236, v213
	v_mov_b32_e32 v248, v220
	ds_bpermute_b32 v238, v247, v221
	v_cmp_neq_f32_e32 vcc, 1.0, v236
	s_cbranch_vccz .Lxa_noresc
	v_pk_mul_f32 v[64:65], v[64:65], v[236:237] op_sel_hi:[1,0]
	v_pk_mul_f32 v[62:63], v[62:63], v[236:237] op_sel_hi:[1,0]
	v_pk_mul_f32 v[60:61], v[60:61], v[236:237] op_sel_hi:[1,0]
	v_pk_mul_f32 v[58:59], v[58:59], v[236:237] op_sel_hi:[1,0]
	v_pk_mul_f32 v[56:57], v[56:57], v[236:237] op_sel_hi:[1,0]
	v_pk_mul_f32 v[54:55], v[54:55], v[236:237] op_sel_hi:[1,0]
	v_pk_mul_f32 v[52:53], v[52:53], v[236:237] op_sel_hi:[1,0]
	v_pk_mul_f32 v[50:51], v[50:51], v[236:237] op_sel_hi:[1,0]
	v_pk_mul_f32 v[48:49], v[48:49], v[236:237] op_sel_hi:[1,0]
	v_pk_mul_f32 v[46:47], v[46:47], v[236:237] op_sel_hi:[1,0]
	v_pk_mul_f32 v[44:45], v[44:45], v[236:237] op_sel_hi:[1,0]
	v_pk_mul_f32 v[42:43], v[42:43], v[236:237] op_sel_hi:[1,0]
	v_pk_mul_f32 v[40:41], v[40:41], v[236:237] op_sel_hi:[1,0]
	v_pk_mul_f32 v[38:39], v[38:39], v[236:237] op_sel_hi:[1,0]
	v_pk_mul_f32 v[36:37], v[36:37], v[236:237] op_sel_hi:[1,0]
	v_pk_mul_f32 v[34:35], v[34:35], v[236:237] op_sel_hi:[1,0]
	v_pk_mul_f32 v[32:33], v[32:33], v[236:237] op_sel_hi:[1,0]
	v_pk_mul_f32 v[30:31], v[30:31], v[236:237] op_sel_hi:[1,0]
	v_pk_mul_f32 v[28:29], v[28:29], v[236:237] op_sel_hi:[1,0]
	v_pk_mul_f32 v[26:27], v[26:27], v[236:237] op_sel_hi:[1,0]
	v_pk_mul_f32 v[24:25], v[24:25], v[236:237] op_sel_hi:[1,0]
	v_pk_mul_f32 v[22:23], v[22:23], v[236:237] op_sel_hi:[1,0]
	v_pk_mul_f32 v[20:21], v[20:21], v[236:237] op_sel_hi:[1,0]
	v_pk_mul_f32 v[18:19], v[18:19], v[236:237] op_sel_hi:[1,0]
	v_pk_mul_f32 v[16:17], v[16:17], v[236:237] op_sel_hi:[1,0]
	v_pk_mul_f32 v[14:15], v[14:15], v[236:237] op_sel_hi:[1,0]
	v_pk_mul_f32 v[12:13], v[12:13], v[236:237] op_sel_hi:[1,0]
	v_pk_mul_f32 v[10:11], v[10:11], v[236:237] op_sel_hi:[1,0]
	v_pk_mul_f32 v[8:9], v[8:9], v[236:237] op_sel_hi:[1,0]
	v_pk_mul_f32 v[6:7], v[6:7], v[236:237] op_sel_hi:[1,0]
	v_pk_mul_f32 v[4:5], v[4:5], v[236:237] op_sel_hi:[1,0]
	v_pk_mul_f32 v[2:3], v[2:3], v[236:237] op_sel_hi:[1,0]
.Lxa_noresc:
	s_waitcnt lgkmcnt(0)
	v_add_f32_e32 v221, v221, v238
	v_fmac_f32_e32 v221, v231, v236
	s_nop 0
	v_mov_b32_e32 v231, v221
	v_cvt_pk_bf16_f32 v66, v66, v67
	v_cvt_pk_bf16_f32 v67, v68, v69
	v_cvt_pk_bf16_f32 v68, v70, v71
	v_cvt_pk_bf16_f32 v69, v72, v73
	v_cvt_pk_bf16_f32 v70, v74, v75
	v_cvt_pk_bf16_f32 v71, v76, v77
	v_cvt_pk_bf16_f32 v72, v78, v79
	v_cvt_pk_bf16_f32 v73, v80, v81
	s_nop 1
	v_mfma_f32_32x32x16_bf16 v[50:65], v[146:149], v[66:69], v[50:65]
	v_mfma_f32_32x32x16_bf16 v[34:49], v[150:153], v[66:69], v[34:49]
	v_mfma_f32_32x32x16_bf16 v[18:33], v[154:157], v[66:69], v[18:33]
	v_mfma_f32_32x32x16_bf16 v[2:17], v[158:161], v[66:69], v[2:17]
	v_mfma_f32_32x32x16_bf16 v[50:65], v[162:165], v[70:73], v[50:65]
	v_mfma_f32_32x32x16_bf16 v[34:49], v[166:169], v[70:73], v[34:49]
	v_mfma_f32_32x32x16_bf16 v[18:33], v[170:173], v[70:73], v[18:33]
	v_mfma_f32_32x32x16_bf16 v[2:17], v[174:177], v[70:73], v[2:17]
	v_add_u32_e32 v180, 0x2000, v180
	v_add_u32_e32 v181, 0x2000, v181
	s_add_i32 s11, s11, 1
	s_cmp_lt_u32 s11, 8
	s_cbranch_scc1 .Lxa_tile
	s_nop 15
	s_branch .LBB0_1510
